# attention items remapped so that the 32 workgroups of one XCD take 32 consecutive items (neighbouring key bands share that XCD's L2)
# speedup vs baseline: 1.0023x; 1.0002x over previous
; __device__ __forceinline__ s16x4 ldtr(LAS const unsigned char* p) { return __builtin_bit_cast(s16x4, __builtin_amdgcn_ds_read_tr16_b64_v4i16((LAS s16x4*)p)); }
; __device__ __forceinline__ void phase_attn(LAS unsigned char* lds, const bf16_t* Z, const float* rel_bias, bf16_t* OG, float* LSE, int S, int tid, int lane, int wave, int G) {
;     ...
; #pragma unroll
;         for (int ks = 0; ks < 5; ++ks) {
;             const int r0 = w16 + 32 * ks + 4 * g4 + tq; int r1 = r0 + 16; r1 = r1 > 255 ? 255 : r1;
; #pragma unroll
;             for (int cc = 0; cc < 8; ++cc) {
;                 const s16x4 lo = ldtr(vimg + off_b(r0, 2 * cc + (tp >> 1)) + 8 * (tp & 1));
;                 const s16x4 hi = ldtr(vimg + off_b(r1, 2 * cc + (tp >> 1)) + 8 * (tp & 1));
.LBB0_244:
	s_or_b64 exec, exec, s[4:5]
	v_readlane_b32 s0, v252, 16
	v_readlane_b32 s1, v252, 17
	s_mov_b32 s80, s67
	s_mov_b32 s79, s63
	s_andn2_b64 vcc, exec, s[0:1]
	s_waitcnt lgkmcnt(0)
	s_barrier
	s_cbranch_vccnz .LBB0_251
	v_lshlrev_b32_e32 v1, 2, v202
	s_add_u32 s28, s88, 0x1fd00c00
	v_and_b32_e32 v3, 12, v1
	v_xor_b32_e32 v1, 16, v192
	v_add_u32_e32 v4, 64, v193
	s_addc_u32 s30, s89, 0
	v_cmp_lt_i32_e32 vcc, v1, v4
	v_xor_b32_e32 v5, 32, v192
	s_add_u32 s34, s88, 0x1fd01800
	v_readlane_b32 s4, v254, 40
	v_cndmask_b32_e32 v1, v192, v1, vcc
	v_cmp_lt_i32_e32 vcc, v5, v4
	s_addc_u32 s36, s89, 0
	v_lshlrev_b32_e32 v50, 2, v148
	s_lshl_b32 s37, s4, 4
	v_cndmask_b32_e32 v4, v192, v5, vcc
	v_bfe_u32 v5, v142, 1, 1
	v_and_b32_e32 v6, 12, v142
	v_lshlrev_b32_e32 v51, 2, v4
	v_or3_b32 v4, v50, v149, s37
	v_or_b32_e32 v7, v148, v6
	v_bitop3_b32 v6, v148, v5, v6 bitop3:0x36
	s_waitcnt vmcnt(0)
	v_lshlrev_b32_e32 v71, 4, v6
	v_min_i32_e32 v6, 0xef, v4
	v_lshlrev_b32_e32 v14, 2, v6
	s_add_i32 s42, 0, 0x10000
	v_and_b32_e32 v14, 12, v14
	v_bfe_u32 v15, v6, 2, 2
	v_or_b32_e32 v17, 2, v5
	v_bitop3_b32 v18, v5, v7, 2 bitop3:0x36
	v_or_b32_e32 v19, 4, v5
	v_bitop3_b32 v20, v5, v7, 4 bitop3:0x36
	v_or_b32_e32 v21, 6, v5
	v_bitop3_b32 v22, v5, v7, 6 bitop3:0x36
	v_or_b32_e32 v23, 8, v5
	v_bitop3_b32 v24, v5, v7, 8 bitop3:0x36
	v_or_b32_e32 v25, 10, v5
	v_bitop3_b32 v26, v5, v7, 10 bitop3:0x36
	v_or_b32_e32 v27, 12, v5
	v_bitop3_b32 v28, v5, v7, 12 bitop3:0x36
	v_or_b32_e32 v29, 14, v5
	v_bitop3_b32 v7, v5, v7, 14 bitop3:0x36
	v_lshlrev_b32_e32 v8, 3, v202
	v_lshl_add_u32 v6, v6, 8, s42
	v_bitop3_b32 v16, v14, v5, v15 bitop3:0x36
	v_lshlrev_b32_e32 v73, 4, v18
	v_bitop3_b32 v18, v14, v17, v15 bitop3:0x36
	v_lshlrev_b32_e32 v74, 4, v20
	v_bitop3_b32 v20, v14, v19, v15 bitop3:0x36
	v_lshlrev_b32_e32 v75, 4, v22
	v_bitop3_b32 v22, v14, v21, v15 bitop3:0x36
	v_lshlrev_b32_e32 v76, 4, v24
	v_bitop3_b32 v24, v14, v23, v15 bitop3:0x36
	v_lshlrev_b32_e32 v77, 4, v26
	v_bitop3_b32 v26, v14, v25, v15 bitop3:0x36
	v_lshlrev_b32_e32 v78, 4, v28
	v_bitop3_b32 v28, v14, v27, v15 bitop3:0x36
	v_lshlrev_b32_e32 v79, 4, v7
	v_bitop3_b32 v7, v14, v29, v15 bitop3:0x36
	v_and_b32_e32 v8, 8, v8
	v_lshl_add_u32 v16, v16, 4, v6
	v_lshl_add_u32 v18, v18, 4, v6
	v_lshl_add_u32 v20, v20, 4, v6
	v_lshl_add_u32 v22, v22, 4, v6
	v_lshl_add_u32 v24, v24, 4, v6
	v_lshl_add_u32 v26, v26, 4, v6
	v_lshl_add_u32 v28, v28, 4, v6
	v_lshl_add_u32 v6, v7, 4, v6
	v_add_u32_e32 v7, 32, v4
	v_add_u32_e32 v9, s42, v8
	v_min_i32_e32 v14, 0xef, v7
	v_lshl_add_u32 v80, v7, 8, v9
	v_lshlrev_b32_e32 v7, 2, v14
	v_and_b32_e32 v7, 12, v7
	v_bfe_u32 v15, v14, 2, 2
	v_lshl_add_u32 v14, v14, 8, s42
	v_bitop3_b32 v30, v7, v5, v15 bitop3:0x36
	v_bitop3_b32 v31, v7, v17, v15 bitop3:0x36
	v_bitop3_b32 v32, v7, v19, v15 bitop3:0x36
	v_bitop3_b32 v33, v7, v21, v15 bitop3:0x36
	v_bitop3_b32 v34, v7, v23, v15 bitop3:0x36
	v_bitop3_b32 v35, v7, v25, v15 bitop3:0x36
	v_bitop3_b32 v36, v7, v27, v15 bitop3:0x36
	v_bitop3_b32 v7, v7, v29, v15 bitop3:0x36
	v_lshl_add_u32 v30, v30, 4, v14
	v_lshl_add_u32 v31, v31, 4, v14
	v_lshl_add_u32 v32, v32, 4, v14
	v_lshl_add_u32 v33, v33, 4, v14
	v_lshl_add_u32 v34, v34, 4, v14
	v_lshl_add_u32 v35, v35, 4, v14
	v_lshl_add_u32 v36, v36, 4, v14
	v_lshl_add_u32 v7, v7, 4, v14
	v_add_u32_e32 v14, 64, v4
	v_min_i32_e32 v15, 0xef, v14
	v_lshl_add_u32 v81, v14, 8, v9
	v_lshlrev_b32_e32 v14, 2, v15
	v_and_b32_e32 v14, 12, v14
	v_bfe_u32 v37, v15, 2, 2
	s_lshl_b32 s0, s4, 5
	v_lshl_add_u32 v15, v15, 8, s42
	v_bitop3_b32 v38, v14, v5, v37 bitop3:0x36
	v_bitop3_b32 v39, v14, v17, v37 bitop3:0x36
	v_bitop3_b32 v40, v14, v19, v37 bitop3:0x36
	v_bitop3_b32 v41, v14, v21, v37 bitop3:0x36
	v_bitop3_b32 v42, v14, v23, v37 bitop3:0x36
	v_bitop3_b32 v43, v14, v25, v37 bitop3:0x36
	v_bitop3_b32 v44, v14, v27, v37 bitop3:0x36
	v_bitop3_b32 v14, v14, v29, v37 bitop3:0x36
	s_or_b32 s1, s0, 4
	v_lshl_add_u32 v38, v38, 4, v15
	v_lshl_add_u32 v39, v39, 4, v15
	v_lshl_add_u32 v40, v40, 4, v15
	v_lshl_add_u32 v41, v41, 4, v15
	v_lshl_add_u32 v42, v42, 4, v15
	v_lshl_add_u32 v43, v43, 4, v15
	v_lshl_add_u32 v44, v44, 4, v15
	v_lshl_add_u32 v14, v14, 4, v15
	v_add_u32_e32 v15, 0x60, v4
	v_or_b32_e32 v64, s1, v148
	s_lshl_b32 s44, s1, 8
	s_or_b32 s1, s0, 8
	v_min_i32_e32 v37, 0xef, v15
	v_or_b32_e32 v65, s1, v148
	s_lshl_b32 s45, s1, 8
	s_or_b32 s1, s0, 12
	v_lshl_add_u32 v82, v15, 8, v9
	v_lshlrev_b32_e32 v15, 2, v37
	v_or_b32_e32 v66, s1, v148
	s_lshl_b32 s46, s1, 8
	s_or_b32 s1, s0, 16
	v_and_b32_e32 v15, 12, v15
	v_bfe_u32 v45, v37, 2, 2
	v_or_b32_e32 v67, s1, v148
; __device__ __forceinline__ void phase_attn(LAS unsigned char* lds, const bf16_t* Z, const float* rel_bias, bf16_t* OG, float* LSE, int S, int tid, int lane, int wave, int G) {
;     ...
;     for (int item = blockIdx.x; item < 3 * PER_GRP; item += G) {
;         const int grp = item / PER_GRP; int idx = item % PER_GRP;
;         const int sh = 2 * grp, L = S >> sh, nblk = L >> 7;
;         const int blk = idx % nblk; idx /= nblk; const int h = idx & 3; idx >>= 2; const int r = idx & ((1 << sh) - 1); const int b = idx >> sh;
;         const int head = grp * 4 + h, i0 = blk * 128;
;         const size_t rowbase = (size_t)b * S + r;
;         const bf16_t* Zq = Z + C_Q + head * 128; const bf16_t* Zk = Z + C_K + head * 128; const bf16_t* Zv = Z + C_V + head * 128;
; #pragma unroll
;         for (int q = 0; q < 8; ++q) {
;             const int br = 32 * wave + 4 * q + (lane >> 4); int fi = i0 - 64 + br; fi = fi < 0 ? 0 : (fi > L - 1 ? L - 1 : fi);
;             const int ch = (lane & 15) ^ (((br & 3) << 2) | ((br >> 2) & 3));
;             const size_t go = (rowbase + ((size_t)fi << sh)) * DIN + 8 * ch;
;             __builtin_amdgcn_global_load_lds((const unsigned*)(Zk + go), (LAS unsigned*)(lds + (32 * wave + 4 * q) * 256), 16, 0, 0);
;             __builtin_amdgcn_global_load_lds((const unsigned*)(Zv + go), (LAS unsigned*)(lds + 65536 + (32 * wave + 4 * q) * 256), 16, 0, 0);
;         }
;         const int q0 = i0 + 16 * wave;
;         bf16x8 qf[4];
; #pragma unroll
;         for (int s = 0; s < 4; ++s) qf[s] = *(const bf16x8*)(Zq + (rowbase + ((size_t)(q0 + c) << sh)) * DIN + 32 * s + 8 * g4);
;         __syncthreads();
;         const int w16 = 16 * wave;
;         f32x4 sa[9];
; #pragma unroll
;         for (int kt = 0; kt < 9; ++kt) { f32x4 acc = (f32x4){0.f, 0.f, 0.f, 0.f};
; #pragma unroll
;             for (int s = 0; s < 4; ++s) { const bf16x8 kf = *(const LAS bf16x8*)(lds + off_b(w16 + 16 * kt + c, 4 * s + g4));
;                 acc = __builtin_amdgcn_mfma_f32_16x16x32_bf16(kf, qf[s], acc, 0, 0, 0); }
;             sa[kt] = acc; }
;         const LAS float* tb = tab + head * 192 + 95 - 64 - c;
;     ...
; #pragma unroll
;         for (int ks = 0; ks < 5; ++ks) {
;             const int r0 = w16 + 32 * ks + 4 * g4 + tq; int r1 = r0 + 16; r1 = r1 > 255 ? 255 : r1;
; #pragma unroll
;             for (int cc = 0; cc < 8; ++cc) {
	s_lshl_b32 s47, s1, 8
	s_or_b32 s1, s0, 20
	v_lshl_add_u32 v37, v37, 8, s42
	v_bitop3_b32 v60, v15, v23, v45 bitop3:0x36
	v_or_b32_e32 v53, s0, v148
	v_or_b32_e32 v68, s1, v148
	s_lshl_b32 s57, s1, 8
	s_or_b32 s1, s0, 24
	s_or_b32 s0, s0, 28
	v_lshl_add_u32 v61, v60, 4, v37
	v_bitop3_b32 v60, v15, v25, v45 bitop3:0x36
	v_bitop3_b32 v10, v50, v142, 15 bitop3:0x78
	v_or_b32_e32 v70, s0, v148
	s_lshl_b32 s59, s0, 8
	s_lshl_b32 s0, s4, 12
	v_lshl_add_u32 v72, v4, 8, v9
	v_bitop3_b32 v46, v15, v5, v45 bitop3:0x36
	v_bitop3_b32 v47, v15, v17, v45 bitop3:0x36
	v_bitop3_b32 v48, v15, v19, v45 bitop3:0x36
	v_bitop3_b32 v49, v15, v21, v45 bitop3:0x36
	v_lshl_add_u32 v62, v60, 4, v37
	v_bitop3_b32 v60, v15, v27, v45 bitop3:0x36
	v_bitop3_b32 v15, v15, v29, v45 bitop3:0x36
	v_add_u32_e32 v4, 0x80, v4
	v_lshlrev_b32_e32 v52, 3, v10
	v_bitop3_b32 v10, v50, v103, 1 bitop3:0x36
	s_add_i32 s0, s0, 0
	v_lshl_add_u32 v46, v46, 4, v37
	v_lshl_add_u32 v47, v47, 4, v37
	v_lshl_add_u32 v48, v48, 4, v37
	v_lshl_add_u32 v49, v49, 4, v37
	v_lshl_add_u32 v63, v60, 4, v37
	v_lshl_add_u32 v15, v15, 4, v37
	v_min_i32_e32 v37, 0xef, v4
	v_lshlrev_b32_e32 v54, 3, v10
	v_bitop3_b32 v10, v50, v103, 2 bitop3:0x36
	v_or_b32_e32 v69, s1, v148
	s_lshl_b32 s58, s1, 8
	v_lshl_add_u32 v11, v103, 8, s0
	v_lshl_add_u32 v83, v4, 8, v9
	v_lshlrev_b32_e32 v4, 2, v37
	v_readlane_b32 s0, v254, 51
	s_lshl_b32 s43, s4, 13
	v_lshlrev_b32_e32 v56, 3, v10
	v_bitop3_b32 v10, v50, v103, 3 bitop3:0x36
	v_and_b32_e32 v4, 12, v4
	v_bfe_u32 v9, v37, 2, 2
	v_readlane_b32 s1, v254, 52
	v_lshlrev_b32_e32 v58, 3, v10
	v_bitop3_b32 v10, v3, v148, v149 bitop3:0x36
	v_bitop3_b32 v12, v3, v152, v149 bitop3:0x36
	v_bitop3_b32 v13, v3, v151, v149 bitop3:0x36
	v_bitop3_b32 v3, v3, v150, v149 bitop3:0x36
	v_lshl_add_u32 v37, v37, 8, s42
	v_bitop3_b32 v5, v4, v5, v9 bitop3:0x36
	v_bitop3_b32 v17, v4, v17, v9 bitop3:0x36
	v_bitop3_b32 v19, v4, v19, v9 bitop3:0x36
	v_bitop3_b32 v21, v4, v21, v9 bitop3:0x36
	v_bitop3_b32 v23, v4, v23, v9 bitop3:0x36
	v_bitop3_b32 v25, v4, v25, v9 bitop3:0x36
	v_bitop3_b32 v27, v4, v27, v9 bitop3:0x36
	v_bitop3_b32 v4, v4, v29, v9 bitop3:0x36
	s_and_b64 s[0:1], s[0:1], exec
	v_lshlrev_b32_e32 v9, 2, v103
	v_lshlrev_b32_e32 v2, 3, v148
	v_lshlrev_b32_e32 v10, 4, v10
	v_lshlrev_b32_e32 v12, 4, v12
	v_lshlrev_b32_e32 v13, 4, v13
	v_lshlrev_b32_e32 v3, 4, v3
	v_lshl_add_u32 v5, v5, 4, v37
	v_lshl_add_u32 v17, v17, 4, v37
	v_lshl_add_u32 v19, v19, 4, v37
	v_lshl_add_u32 v21, v21, 4, v37
	v_lshl_add_u32 v23, v23, 4, v37
	v_lshl_add_u32 v25, v25, 4, v37
	v_lshl_add_u32 v27, v27, 4, v37
	v_lshl_add_u32 v4, v4, 4, v37
	v_sub_u32_e32 v9, 0, v9
	s_mov_b32 s0, 0x20800
	v_lshlrev_b32_e32 v1, 2, v1
	v_cmp_gt_u32_e64 s[40:41], 16, v202
	v_mov_b32_e32 v55, v0
	v_mov_b32_e32 v57, v0
	v_mov_b32_e32 v59, v0
	s_cselect_b32 s60, 11, 12
	v_or_b32_e32 v84, 0xffffffc0, v50
	v_or_b32_e32 v85, 0xffffffd0, v50
	v_or_b32_e32 v86, 0xffffffe0, v50
	v_or_b32_e32 v87, -16, v50
	v_or_b32_e32 v88, 16, v50
	v_or_b32_e32 v89, 32, v50
	v_or_b32_e32 v90, 48, v50
	v_or_b32_e32 v91, 64, v50
	v_add3_u32 v92, v9, v143, s0
	v_lshlrev_b32_e32 v60, 1, v2
	v_add_u32_e32 v93, v11, v10
	v_add_u32_e32 v94, v11, v12
	v_add_u32_e32 v95, v11, v13
	v_add_u32_e32 v96, v11, v3
	v_add_u32_e32 v97, v16, v8
	v_add_u32_e32 v98, v18, v8
	v_add_u32_e32 v99, v20, v8
	v_add_u32_e32 v100, v22, v8
	v_add_u32_e32 v101, v24, v8
	v_add_u32_e32 v102, v26, v8
	v_add_u32_e32 v104, v28, v8
	v_add_u32_e32 v105, v6, v8
	v_add_u32_e32 v106, v30, v8
	v_add_u32_e32 v107, v31, v8
	v_add_u32_e32 v108, v32, v8
	v_add_u32_e32 v109, v33, v8
	v_add_u32_e32 v110, v34, v8
	v_add_u32_e32 v111, v35, v8
	v_add_u32_e32 v112, v36, v8
	v_add_u32_e32 v113, v7, v8
	v_add_u32_e32 v114, v38, v8
	v_add_u32_e32 v115, v39, v8
	v_add_u32_e32 v116, v40, v8
	v_add_u32_e32 v117, v41, v8
	v_add_u32_e32 v118, v42, v8
	v_add_u32_e32 v119, v43, v8
	v_add_u32_e32 v120, v44, v8
	v_add_u32_e32 v121, v14, v8
	v_add_u32_e32 v122, v46, v8
	v_add_u32_e32 v123, v47, v8
	v_add_u32_e32 v124, v48, v8
	v_add_u32_e32 v125, v49, v8
	v_add_u32_e32 v126, v61, v8
	v_add_u32_e32 v127, v62, v8
	v_add_u32_e32 v128, v63, v8
	v_add_u32_e32 v129, v15, v8
	v_add_u32_e32 v142, v5, v8
	v_add_u32_e32 v143, v17, v8
	v_add_u32_e32 v144, v19, v8
	v_add_u32_e32 v145, v21, v8
	v_add_u32_e32 v146, v23, v8
	v_add_u32_e32 v147, v25, v8
	v_add_u32_e32 v148, v27, v8
	v_add_u32_e32 v149, v4, v8
	s_and_b32 s63, s2, 7
	s_lshl_b32 s63, s63, 5
	s_lshr_b32 s0, s2, 3
	s_or_b32 s63, s63, s0
	s_cmpk_eq_i32 s52, 0x100
	s_cselect_b32 s63, s63, s2
	s_branch .LBB0_247

; #define PG8_STAGE(bufoff, gbase, voff) do { _Pragma("unroll") for (int _i = 0; _i < 2; ++_i) \
;         __builtin_amdgcn_global_load_lds((const unsigned*)((const char*)(gbase) + (voff)[_i]), (PG8_LAS unsigned*)(lds + (bufoff) + ldsw + _i * 8192), 16, 0, 0); } while (0)
; #define PG8_LDA(dst, b, h) do { _Pragma("unroll") for (int m = 0; m < 4; ++m) _Pragma("unroll") for (int k = 0; k < 2; ++k) dst[m][k] = *(const PG8_LAS bf16x8*)(lds + PG8_SA(b, h) + aoff + m * 2048 + k * 1024); } while (0)
; #define PG8_LDB(dst, b, h) do { _Pragma("unroll") for (int n = 0; n < 2; ++n) _Pragma("unroll") for (int k = 0; k < 2; ++k) dst[n][k] = *(const PG8_LAS bf16x8*)(lds + PG8_SB(b, h) + boff + n * 2048 + k * 1024); } while (0)
; #define PG8_MMA(ai, bj, At, Bt) do { __builtin_amdgcn_s_setprio(1); _Pragma("unroll") for (int m = 0; m < 4; ++m) _Pragma("unroll") for (int n = 0; n < 2; ++n) _Pragma("unroll") for (int k = 0; k < 2; ++k) \
;         acc[ai][bj][m][n] = __builtin_amdgcn_mfma_f32_16x16x32_bf16(Bt[n][k], At[m][k], acc[ai][bj][m][n], 0, 0, 0); __builtin_amdgcn_s_setprio(0); } while (0)
; #define PG8_WAIT_V(n) asm volatile("s_waitcnt vmcnt(" #n ")" ::: "memory")
; #define PG8_BAR __builtin_amdgcn_s_barrier()
; template <class Epi, class Sched, bool ALIGN_EPI = false, bool SP2 = false>
; __device__ __forceinline__ void gemm_phase(PG8_LAS unsigned char* lds, const Gemm g, const Sched& S, const Epi& E) {
;     ...
;         for (int t = 0; t < nt; t += 2) {
;             const bool last = (t == nt - 2);
;             const char* a1 = cA + (size_t)(t + 1) * kstep;
;             const char* a2 = last ? nA : cA + (size_t)(t + 2) * kstep; const char* b2 = last ? nB : cB + (size_t)(t + 2) * kstep;
;             const char* a3 = a2 + kstep; const char* b3 = b2 + kstep;
;             if (last && has_next) S.a_ready(nxt);
;             if constexpr (SP2) {
;             PG8_LDB(B0, 0, 0); PG8_LDB(B1, 0, 1); PG8_SCHED; PG8_LDA(At, 0, 0); PG8_STAGE(PG8_SA(1, 1), a1 + hstep, voffA);
;             PG8_WAIT_V(8); PG8_WAIT_L(0); PG8_BAR; PG8_MMA(0, 0, At, B0); PG8_MMA(0, 1, At, B1); PG8_BAR; PG8_SCHED;
;             PG8_LDA(At, 0, 1); PG8_STAGE(PG8_SB(0, 0), b2, voffB); PG8_STAGE(PG8_SB(0, 1), b2 + hstep, voffB); PG8_STAGE(PG8_SA(0, 0), a2, voffA);
;             PG8_WAIT_V(8); PG8_WAIT_L(0); PG8_BAR; PG8_MMA(1, 0, At, B0); PG8_MMA(1, 1, At, B1); PG8_BAR; PG8_SCHED;
.LBB0_281:
	s_add_u32 s18, s36, 0xfff80080
	s_addc_u32 s19, s37, -1
	s_add_i32 s73, 0, 0x10000
	s_cmp_eq_u32 s67, 28
	s_cselect_b32 s43, s9, s19
	s_cselect_b32 s42, s59, s18
	v_add_u32_e32 v163, s73, v160
	s_cselect_b32 s19, s7, s63
	s_cselect_b32 s18, s60, s62
	s_add_i32 s76, 0, 0x14000
	ds_read_b128 v[156:159], v163
	ds_read_b128 v[164:167], v163 offset:1024
	ds_read_b128 v[168:171], v163 offset:2048
	ds_read_b128 v[172:175], v163 offset:3072
	v_add_u32_e32 v163, s76, v160
	ds_read_b128 v[176:179], v163
	ds_read_b128 v[180:183], v163 offset:1024
	ds_read_b128 v[184:187], v163 offset:2048
	ds_read_b128 v[204:207], v163 offset:3072
	v_lshl_add_u64 v[240:241], s[36:37], 0, v[152:153]
	s_add_i32 m0, s30, 0xc000
	ds_read_b128 v[208:211], v162
	ds_read_b128 v[212:215], v162 offset:1024
	ds_read_b128 v[216:219], v162 offset:2048
	ds_read_b128 v[220:223], v162 offset:3072
	ds_read_b128 v[224:227], v162 offset:4096
	ds_read_b128 v[228:231], v162 offset:5120
	ds_read_b128 v[232:235], v162 offset:6144
	ds_read_b128 v[236:239], v162 offset:7168
	global_load_lds_dwordx4 v[240:241], off
	v_lshl_add_u64 v[240:241], s[36:37], 0, v[154:155]
	s_add_i32 m0, s30, 0xe000
	s_nop 0
	global_load_lds_dwordx4 v[240:241], off
	s_nop 0
	s_nop 0
	s_waitcnt vmcnt(8)
	s_waitcnt lgkmcnt(0)
	s_barrier
	s_setprio 1
	v_mfma_f32_16x16x32_bf16 v[126:129], v[156:159], v[208:211], v[126:129]
	v_mfma_f32_16x16x32_bf16 v[122:125], v[168:171], v[208:211], v[122:125]
	v_mfma_f32_16x16x32_bf16 v[110:113], v[156:159], v[216:219], v[110:113]
	v_mfma_f32_16x16x32_bf16 v[106:109], v[168:171], v[216:219], v[106:109]
	v_mfma_f32_16x16x32_bf16 v[94:97], v[156:159], v[224:227], v[94:97]
	v_mfma_f32_16x16x32_bf16 v[90:93], v[168:171], v[224:227], v[90:93]
	v_mfma_f32_16x16x32_bf16 v[78:81], v[156:159], v[232:235], v[78:81]
	v_mfma_f32_16x16x32_bf16 v[74:77], v[168:171], v[232:235], v[74:77]
	s_setprio 0
	s_setprio 1
	v_mfma_f32_16x16x32_bf16 v[126:129], v[164:167], v[212:215], v[126:129]
	v_mfma_f32_16x16x32_bf16 v[122:125], v[172:175], v[212:215], v[122:125]
	v_mfma_f32_16x16x32_bf16 v[110:113], v[164:167], v[220:223], v[110:113]
	v_mfma_f32_16x16x32_bf16 v[106:109], v[172:175], v[220:223], v[106:109]
	v_mfma_f32_16x16x32_bf16 v[94:97], v[164:167], v[228:231], v[94:97]
	v_mfma_f32_16x16x32_bf16 v[90:93], v[172:175], v[228:231], v[90:93]
	v_mfma_f32_16x16x32_bf16 v[78:81], v[164:167], v[236:239], v[78:81]
	v_mfma_f32_16x16x32_bf16 v[74:77], v[172:175], v[236:239], v[74:77]
	s_setprio 0
	s_setprio 1
	v_mfma_f32_16x16x32_bf16 v[118:121], v[176:179], v[208:211], v[118:121]
	v_mfma_f32_16x16x32_bf16 v[114:117], v[184:187], v[208:211], v[114:117]
	v_mfma_f32_16x16x32_bf16 v[102:105], v[176:179], v[216:219], v[102:105]
	v_mfma_f32_16x16x32_bf16 v[98:101], v[184:187], v[216:219], v[98:101]
	v_mfma_f32_16x16x32_bf16 v[86:89], v[176:179], v[224:227], v[86:89]
	v_mfma_f32_16x16x32_bf16 v[82:85], v[184:187], v[224:227], v[82:85]
	v_mfma_f32_16x16x32_bf16 v[70:73], v[176:179], v[232:235], v[70:73]
	v_mfma_f32_16x16x32_bf16 v[66:69], v[184:187], v[232:235], v[66:69]
	s_setprio 0
	s_setprio 1
	v_mfma_f32_16x16x32_bf16 v[118:121], v[180:183], v[212:215], v[118:121]
	v_mfma_f32_16x16x32_bf16 v[114:117], v[204:207], v[212:215], v[114:117]
	v_mfma_f32_16x16x32_bf16 v[102:105], v[180:183], v[220:223], v[102:105]
	v_mfma_f32_16x16x32_bf16 v[98:101], v[204:207], v[220:223], v[98:101]
	v_mfma_f32_16x16x32_bf16 v[86:89], v[180:183], v[228:231], v[86:89]
	v_mfma_f32_16x16x32_bf16 v[82:85], v[204:207], v[228:231], v[82:85]
	v_mfma_f32_16x16x32_bf16 v[70:73], v[180:183], v[236:239], v[70:73]
	v_mfma_f32_16x16x32_bf16 v[66:69], v[204:207], v[236:239], v[66:69]
	s_setprio 0
	s_barrier
	s_add_i32 s73, s73, s28
	v_lshl_add_u64 v[240:241], s[18:19], 0, v[146:147]
	s_mov_b32 m0, s73
	ds_read_b128 v[208:211], v162 offset:16384
	ds_read_b128 v[212:215], v162 offset:17408
	ds_read_b128 v[216:219], v162 offset:18432
	ds_read_b128 v[220:223], v162 offset:19456
	ds_read_b128 v[224:227], v162 offset:20480
	ds_read_b128 v[228:231], v162 offset:21504
	ds_read_b128 v[232:235], v162 offset:22528
	ds_read_b128 v[236:239], v162 offset:23552
	global_load_lds_dwordx4 v[240:241], off
	s_add_i32 m0, s73, 0x2000
	s_add_u32 s78, s18, 0x80000
	v_lshl_add_u64 v[242:243], s[18:19], 0, v[142:143]
	s_addc_u32 s79, s19, 0
	s_add_i32 s73, s76, s28
	global_load_lds_dwordx4 v[242:243], off
	v_lshl_add_u64 v[244:245], s[78:79], 0, v[146:147]
	s_mov_b32 m0, s73
	v_lshl_add_u64 v[246:247], s[42:43], 0, v[144:145]
	global_load_lds_dwordx4 v[244:245], off
	v_lshl_add_u64 v[244:245], s[78:79], 0, v[142:143]
	s_add_i32 m0, s73, 0x2000
	s_nop 0
	global_load_lds_dwordx4 v[244:245], off
	v_lshl_add_u64 v[244:245], s[42:43], 0, v[148:149]
	s_mov_b32 m0, s30
	s_nop 0
	global_load_lds_dwordx4 v[244:245], off
	s_mov_b32 m0, s34
	s_nop 0
	global_load_lds_dwordx4 v[246:247], off
	s_waitcnt vmcnt(8)
	s_waitcnt lgkmcnt(0)
	s_barrier
; #define PG8_STAGE(bufoff, gbase, voff) do { _Pragma("unroll") for (int _i = 0; _i < 2; ++_i) \
;         __builtin_amdgcn_global_load_lds((const unsigned*)((const char*)(gbase) + (voff)[_i]), (PG8_LAS unsigned*)(lds + (bufoff) + ldsw + _i * 8192), 16, 0, 0); } while (0)
; #define PG8_LDA(dst, b, h) do { _Pragma("unroll") for (int m = 0; m < 4; ++m) _Pragma("unroll") for (int k = 0; k < 2; ++k) dst[m][k] = *(const PG8_LAS bf16x8*)(lds + PG8_SA(b, h) + aoff + m * 2048 + k * 1024); } while (0)
; #define PG8_LDB(dst, b, h) do { _Pragma("unroll") for (int n = 0; n < 2; ++n) _Pragma("unroll") for (int k = 0; k < 2; ++k) dst[n][k] = *(const PG8_LAS bf16x8*)(lds + PG8_SB(b, h) + boff + n * 2048 + k * 1024); } while (0)
; #define PG8_MMA(ai, bj, At, Bt) do { __builtin_amdgcn_s_setprio(1); _Pragma("unroll") for (int m = 0; m < 4; ++m) _Pragma("unroll") for (int n = 0; n < 2; ++n) _Pragma("unroll") for (int k = 0; k < 2; ++k) \
;         acc[ai][bj][m][n] = __builtin_amdgcn_mfma_f32_16x16x32_bf16(Bt[n][k], At[m][k], acc[ai][bj][m][n], 0, 0, 0); __builtin_amdgcn_s_setprio(0); } while (0)
; #define PG8_WAIT_V(n) asm volatile("s_waitcnt vmcnt(" #n ")" ::: "memory")
; #define PG8_WAIT_L(n) asm volatile("s_waitcnt lgkmcnt(" #n ")" ::: "memory")
; #define PG8_BAR __builtin_amdgcn_s_barrier()
; #define PG8_SCHED __builtin_amdgcn_sched_barrier(0)
; template <class Epi, class Sched, bool ALIGN_EPI = false, bool SP2 = false>
; __device__ __forceinline__ void gemm_phase(PG8_LAS unsigned char* lds, const Gemm g, const Sched& S, const Epi& E) {
;     ...
;             PG8_WAIT_V(8); PG8_WAIT_L(0); PG8_BAR; PG8_MMA(1, 0, At, B0); PG8_MMA(1, 1, At, B1); PG8_BAR; PG8_SCHED;
;             PG8_LDB(B0, 1, 0); PG8_LDB(B1, 1, 1); PG8_SCHED; PG8_LDA(At, 1, 0); PG8_STAGE(PG8_SA(0, 1), a2 + hstep, voffA);
;             PG8_WAIT_V(8); PG8_WAIT_L(0); PG8_BAR; PG8_MMA(0, 0, At, B0); PG8_MMA(0, 1, At, B1); PG8_BAR; PG8_SCHED;
	s_setprio 1
	v_mfma_f32_16x16x32_bf16 v[62:65], v[156:159], v[208:211], v[62:65]
	v_mfma_f32_16x16x32_bf16 v[58:61], v[168:171], v[208:211], v[58:61]
	v_mfma_f32_16x16x32_bf16 v[46:49], v[156:159], v[216:219], v[46:49]
	v_mfma_f32_16x16x32_bf16 v[42:45], v[168:171], v[216:219], v[42:45]
	v_mfma_f32_16x16x32_bf16 v[30:33], v[156:159], v[224:227], v[30:33]
	v_mfma_f32_16x16x32_bf16 v[26:29], v[168:171], v[224:227], v[26:29]
	v_mfma_f32_16x16x32_bf16 v[14:17], v[156:159], v[232:235], v[14:17]
	v_mfma_f32_16x16x32_bf16 v[10:13], v[168:171], v[232:235], v[10:13]
	s_setprio 0
	s_setprio 1
	v_mfma_f32_16x16x32_bf16 v[62:65], v[164:167], v[212:215], v[62:65]
	v_mfma_f32_16x16x32_bf16 v[58:61], v[172:175], v[212:215], v[58:61]
	v_mfma_f32_16x16x32_bf16 v[46:49], v[164:167], v[220:223], v[46:49]
	v_mfma_f32_16x16x32_bf16 v[42:45], v[172:175], v[220:223], v[42:45]
	v_mfma_f32_16x16x32_bf16 v[30:33], v[164:167], v[228:231], v[30:33]
	v_mfma_f32_16x16x32_bf16 v[26:29], v[172:175], v[228:231], v[26:29]
	v_mfma_f32_16x16x32_bf16 v[14:17], v[164:167], v[236:239], v[14:17]
	v_mfma_f32_16x16x32_bf16 v[10:13], v[172:175], v[236:239], v[10:13]
	s_setprio 0
	s_setprio 1
	v_mfma_f32_16x16x32_bf16 v[54:57], v[176:179], v[208:211], v[54:57]
	v_mfma_f32_16x16x32_bf16 v[50:53], v[184:187], v[208:211], v[50:53]
	v_mfma_f32_16x16x32_bf16 v[38:41], v[176:179], v[216:219], v[38:41]
	v_mfma_f32_16x16x32_bf16 v[34:37], v[184:187], v[216:219], v[34:37]
	v_mfma_f32_16x16x32_bf16 v[22:25], v[176:179], v[224:227], v[22:25]
	v_mfma_f32_16x16x32_bf16 v[18:21], v[184:187], v[224:227], v[18:21]
	v_mfma_f32_16x16x32_bf16 v[6:9], v[176:179], v[232:235], v[6:9]
	v_mfma_f32_16x16x32_bf16 v[2:5], v[184:187], v[232:235], v[2:5]
	s_setprio 0
	s_setprio 1
	v_mfma_f32_16x16x32_bf16 v[54:57], v[180:183], v[212:215], v[54:57]
	v_mfma_f32_16x16x32_bf16 v[50:53], v[204:207], v[212:215], v[50:53]
	v_mfma_f32_16x16x32_bf16 v[38:41], v[180:183], v[220:223], v[38:41]
	v_mfma_f32_16x16x32_bf16 v[34:37], v[204:207], v[220:223], v[34:37]
	v_mfma_f32_16x16x32_bf16 v[22:25], v[180:183], v[228:231], v[22:25]
	v_mfma_f32_16x16x32_bf16 v[18:21], v[204:207], v[228:231], v[18:21]
	v_mfma_f32_16x16x32_bf16 v[6:9], v[180:183], v[236:239], v[6:9]
	v_mfma_f32_16x16x32_bf16 v[2:5], v[204:207], v[236:239], v[2:5]
	s_setprio 0
	s_barrier
	s_add_i32 s73, 0, 0x18000
	v_add_u32_e32 v163, s73, v160
	s_add_i32 s76, 0, 0x1c000
	ds_read_b128 v[156:159], v163
	ds_read_b128 v[164:167], v163 offset:1024
	ds_read_b128 v[168:171], v163 offset:2048
	ds_read_b128 v[172:175], v163 offset:3072
	v_add_u32_e32 v163, s76, v160
	ds_read_b128 v[176:179], v163
	ds_read_b128 v[180:183], v163 offset:1024
	ds_read_b128 v[184:187], v163 offset:2048
	ds_read_b128 v[204:207], v163 offset:3072
	s_add_u32 s42, s42, 0x80000
	s_addc_u32 s43, s43, 0
	s_mov_b32 m0, s44
	v_lshl_add_u64 v[248:249], s[42:43], 0, v[148:149]
	ds_read_b128 v[208:211], v162 offset:32768
	ds_read_b128 v[212:215], v162 offset:33792
	ds_read_b128 v[216:219], v162 offset:34816
	ds_read_b128 v[220:223], v162 offset:35840
	ds_read_b128 v[224:227], v162 offset:36864
	ds_read_b128 v[228:231], v162 offset:37888
	ds_read_b128 v[232:235], v162 offset:38912
	ds_read_b128 v[236:239], v162 offset:39936
	global_load_lds_dwordx4 v[248:249], off
	v_lshl_add_u64 v[248:249], s[42:43], 0, v[144:145]
	s_mov_b32 m0, s45
	s_nop 0
	global_load_lds_dwordx4 v[248:249], off
	s_waitcnt vmcnt(8)
	s_waitcnt lgkmcnt(0)
	s_barrier
	s_setprio 1
	v_mfma_f32_16x16x32_bf16 v[126:129], v[156:159], v[208:211], v[126:129]
	v_mfma_f32_16x16x32_bf16 v[122:125], v[168:171], v[208:211], v[122:125]
	v_mfma_f32_16x16x32_bf16 v[110:113], v[156:159], v[216:219], v[110:113]
	v_mfma_f32_16x16x32_bf16 v[106:109], v[168:171], v[216:219], v[106:109]
	v_mfma_f32_16x16x32_bf16 v[94:97], v[156:159], v[224:227], v[94:97]
	v_mfma_f32_16x16x32_bf16 v[90:93], v[168:171], v[224:227], v[90:93]
	v_mfma_f32_16x16x32_bf16 v[78:81], v[156:159], v[232:235], v[78:81]
	v_mfma_f32_16x16x32_bf16 v[74:77], v[168:171], v[232:235], v[74:77]
	s_setprio 0
	s_setprio 1
	v_mfma_f32_16x16x32_bf16 v[126:129], v[164:167], v[212:215], v[126:129]
	v_mfma_f32_16x16x32_bf16 v[122:125], v[172:175], v[212:215], v[122:125]
	v_mfma_f32_16x16x32_bf16 v[110:113], v[164:167], v[220:223], v[110:113]
	v_mfma_f32_16x16x32_bf16 v[106:109], v[172:175], v[220:223], v[106:109]
	v_mfma_f32_16x16x32_bf16 v[94:97], v[164:167], v[228:231], v[94:97]
	v_mfma_f32_16x16x32_bf16 v[90:93], v[172:175], v[228:231], v[90:93]
	v_mfma_f32_16x16x32_bf16 v[78:81], v[164:167], v[236:239], v[78:81]
	v_mfma_f32_16x16x32_bf16 v[74:77], v[172:175], v[236:239], v[74:77]
	s_setprio 0
	s_setprio 1
	v_mfma_f32_16x16x32_bf16 v[118:121], v[176:179], v[208:211], v[118:121]
	v_mfma_f32_16x16x32_bf16 v[114:117], v[184:187], v[208:211], v[114:117]
	v_mfma_f32_16x16x32_bf16 v[102:105], v[176:179], v[216:219], v[102:105]
	v_mfma_f32_16x16x32_bf16 v[98:101], v[184:187], v[216:219], v[98:101]
	v_mfma_f32_16x16x32_bf16 v[86:89], v[176:179], v[224:227], v[86:89]
	v_mfma_f32_16x16x32_bf16 v[82:85], v[184:187], v[224:227], v[82:85]
	v_mfma_f32_16x16x32_bf16 v[70:73], v[176:179], v[232:235], v[70:73]
	v_mfma_f32_16x16x32_bf16 v[66:69], v[184:187], v[232:235], v[66:69]
	s_setprio 0
	s_setprio 1
	v_mfma_f32_16x16x32_bf16 v[118:121], v[180:183], v[212:215], v[118:121]
	v_mfma_f32_16x16x32_bf16 v[114:117], v[204:207], v[212:215], v[114:117]
	v_mfma_f32_16x16x32_bf16 v[102:105], v[180:183], v[220:223], v[102:105]
	v_mfma_f32_16x16x32_bf16 v[98:101], v[204:207], v[220:223], v[98:101]
	v_mfma_f32_16x16x32_bf16 v[86:89], v[180:183], v[228:231], v[86:89]
	v_mfma_f32_16x16x32_bf16 v[82:85], v[204:207], v[228:231], v[82:85]
	v_mfma_f32_16x16x32_bf16 v[70:73], v[180:183], v[236:239], v[70:73]
	v_mfma_f32_16x16x32_bf16 v[66:69], v[204:207], v[236:239], v[66:69]
	s_setprio 0
	s_barrier
; #define PG8_STAGE(bufoff, gbase, voff) do { _Pragma("unroll") for (int _i = 0; _i < 2; ++_i) \
;         __builtin_amdgcn_global_load_lds((const unsigned*)((const char*)(gbase) + (voff)[_i]), (PG8_LAS unsigned*)(lds + (bufoff) + ldsw + _i * 8192), 16, 0, 0); } while (0)
; #define PG8_LDA(dst, b, h) do { _Pragma("unroll") for (int m = 0; m < 4; ++m) _Pragma("unroll") for (int k = 0; k < 2; ++k) dst[m][k] = *(const PG8_LAS bf16x8*)(lds + PG8_SA(b, h) + aoff + m * 2048 + k * 1024); } while (0)
; #define PG8_MMA(ai, bj, At, Bt) do { __builtin_amdgcn_s_setprio(1); _Pragma("unroll") for (int m = 0; m < 4; ++m) _Pragma("unroll") for (int n = 0; n < 2; ++n) _Pragma("unroll") for (int k = 0; k < 2; ++k) \
;         acc[ai][bj][m][n] = __builtin_amdgcn_mfma_f32_16x16x32_bf16(Bt[n][k], At[m][k], acc[ai][bj][m][n], 0, 0, 0); __builtin_amdgcn_s_setprio(0); } while (0)
; #define PG8_WAIT_V(n) asm volatile("s_waitcnt vmcnt(" #n ")" ::: "memory")
; #define PG8_WAIT_L(n) asm volatile("s_waitcnt lgkmcnt(" #n ")" ::: "memory")
; #define PG8_BAR __builtin_amdgcn_s_barrier()
; #define PG8_SCHED __builtin_amdgcn_sched_barrier(0)
; template <class Epi, class Sched, bool ALIGN_EPI = false, bool SP2 = false>
; __device__ __forceinline__ void gemm_phase(PG8_LAS unsigned char* lds, const Gemm g, const Sched& S, const Epi& E) {
;     ...
;         for (int t = 0; t < nt; t += 2) {
;             const bool last = (t == nt - 2);
;             const char* a1 = cA + (size_t)(t + 1) * kstep;
;             const char* a2 = last ? nA : cA + (size_t)(t + 2) * kstep; const char* b2 = last ? nB : cB + (size_t)(t + 2) * kstep;
;     ...
;             PG8_LDA(At, 1, 1); PG8_STAGE(PG8_SB(1, 0), b3, voffB); PG8_STAGE(PG8_SB(1, 1), b3 + hstep, voffB); PG8_STAGE(PG8_SA(1, 0), a3, voffA);
;             PG8_WAIT_V(8); PG8_WAIT_L(0); PG8_BAR; PG8_MMA(1, 0, At, B0); PG8_MMA(1, 1, At, B1); PG8_BAR; PG8_SCHED;
	s_add_i32 s42, s73, s28
	v_lshl_add_u64 v[240:241], v[240:241], 0, s[68:69]
	s_mov_b32 m0, s42
	ds_read_b128 v[208:211], v162 offset:49152
	ds_read_b128 v[212:215], v162 offset:50176
	ds_read_b128 v[216:219], v162 offset:51200
	ds_read_b128 v[220:223], v162 offset:52224
	ds_read_b128 v[224:227], v162 offset:53248
	ds_read_b128 v[228:231], v162 offset:54272
	ds_read_b128 v[232:235], v162 offset:55296
	ds_read_b128 v[236:239], v162 offset:56320
	global_load_lds_dwordx4 v[240:241], off
	s_add_i32 m0, s42, 0x2000
	s_add_u32 s18, s18, 0x80080
	v_lshl_add_u64 v[240:241], v[242:243], 0, s[68:69]
	s_addc_u32 s19, s19, 0
	s_add_i32 s42, s76, s28
	global_load_lds_dwordx4 v[240:241], off
	v_lshl_add_u64 v[240:241], s[18:19], 0, v[146:147]
	s_mov_b32 m0, s42
	s_nop 0
	global_load_lds_dwordx4 v[240:241], off
	v_lshl_add_u64 v[240:241], s[18:19], 0, v[142:143]
	s_add_i32 m0, s42, 0x2000
	s_nop 0
	global_load_lds_dwordx4 v[240:241], off
	v_lshl_add_u64 v[240:241], v[244:245], 0, s[68:69]
	s_mov_b32 m0, s46
	s_nop 0
	global_load_lds_dwordx4 v[240:241], off
	v_lshl_add_u64 v[240:241], v[246:247], 0, s[68:69]
	s_mov_b32 m0, s47
	s_nop 0
	global_load_lds_dwordx4 v[240:241], off
	s_nop 0
	s_waitcnt vmcnt(8)
	s_waitcnt lgkmcnt(0)
	s_barrier
	s_setprio 1
	v_mfma_f32_16x16x32_bf16 v[62:65], v[156:159], v[208:211], v[62:65]
	v_mfma_f32_16x16x32_bf16 v[58:61], v[168:171], v[208:211], v[58:61]
	v_mfma_f32_16x16x32_bf16 v[46:49], v[156:159], v[216:219], v[46:49]
	v_mfma_f32_16x16x32_bf16 v[42:45], v[168:171], v[216:219], v[42:45]
	v_mfma_f32_16x16x32_bf16 v[30:33], v[156:159], v[224:227], v[30:33]
	v_mfma_f32_16x16x32_bf16 v[26:29], v[168:171], v[224:227], v[26:29]
	v_mfma_f32_16x16x32_bf16 v[14:17], v[156:159], v[232:235], v[14:17]
	v_mfma_f32_16x16x32_bf16 v[10:13], v[168:171], v[232:235], v[10:13]
	s_setprio 0
	s_setprio 1
	v_mfma_f32_16x16x32_bf16 v[62:65], v[164:167], v[212:215], v[62:65]
	v_mfma_f32_16x16x32_bf16 v[58:61], v[172:175], v[212:215], v[58:61]
	v_mfma_f32_16x16x32_bf16 v[46:49], v[164:167], v[220:223], v[46:49]
	v_mfma_f32_16x16x32_bf16 v[42:45], v[172:175], v[220:223], v[42:45]
	v_mfma_f32_16x16x32_bf16 v[30:33], v[164:167], v[228:231], v[30:33]
	v_mfma_f32_16x16x32_bf16 v[26:29], v[172:175], v[228:231], v[26:29]
	v_mfma_f32_16x16x32_bf16 v[14:17], v[164:167], v[236:239], v[14:17]
	v_mfma_f32_16x16x32_bf16 v[10:13], v[172:175], v[236:239], v[10:13]
	s_setprio 0
	s_setprio 1
	v_mfma_f32_16x16x32_bf16 v[54:57], v[176:179], v[208:211], v[54:57]
	v_mfma_f32_16x16x32_bf16 v[50:53], v[184:187], v[208:211], v[50:53]
	v_mfma_f32_16x16x32_bf16 v[38:41], v[176:179], v[216:219], v[38:41]
	v_mfma_f32_16x16x32_bf16 v[34:37], v[184:187], v[216:219], v[34:37]
	v_mfma_f32_16x16x32_bf16 v[22:25], v[176:179], v[224:227], v[22:25]
	v_mfma_f32_16x16x32_bf16 v[18:21], v[184:187], v[224:227], v[18:21]
	v_mfma_f32_16x16x32_bf16 v[6:9], v[176:179], v[232:235], v[6:9]
	v_mfma_f32_16x16x32_bf16 v[2:5], v[184:187], v[232:235], v[2:5]
	s_setprio 0
	s_setprio 1
	v_mfma_f32_16x16x32_bf16 v[54:57], v[180:183], v[212:215], v[54:57]
	v_mfma_f32_16x16x32_bf16 v[50:53], v[204:207], v[212:215], v[50:53]
	v_mfma_f32_16x16x32_bf16 v[38:41], v[180:183], v[220:223], v[38:41]
	v_mfma_f32_16x16x32_bf16 v[34:37], v[204:207], v[220:223], v[34:37]
	v_mfma_f32_16x16x32_bf16 v[22:25], v[180:183], v[228:231], v[22:25]
	v_mfma_f32_16x16x32_bf16 v[18:21], v[204:207], v[228:231], v[18:21]
	v_mfma_f32_16x16x32_bf16 v[6:9], v[180:183], v[236:239], v[6:9]
	v_mfma_f32_16x16x32_bf16 v[2:5], v[204:207], v[236:239], v[2:5]
	s_setprio 0
	s_barrier
	s_add_i32 s67, s67, 2
	s_add_u32 s36, s36, 0x100
	s_addc_u32 s37, s37, 0
	s_add_u32 s62, s62, 0x100
	s_addc_u32 s63, s63, 0
	s_cmp_gt_u32 s67, 29
	s_cbranch_scc0 .LBB0_281
	s_and_b64 vcc, exec, s[4:5]
	s_cbranch_vccnz .LBB0_286
	s_cmp_lt_i32 s57, 30
	s_mov_b64 s[18:19], -1
	s_cbranch_scc1 .LBB0_287
